# V-transpose tiles (post1/post2): 8 row loads issued together with counted vmcnt before the LDS writes
# speedup vs baseline: 1.0120x; 1.0120x over previous
; #define LAS __attribute__((address_space(3)))
; #define LDS_WAIT() asm volatile("s_waitcnt lgkmcnt(0)" ::: "memory")
; __device__ __forceinline__ void vt_tile(const bf16_t* src, int spitch, bf16_t* dst, LAS bf16_t* scr, int lane) {
; #pragma unroll
;     for (int i = 0; i < 8; ++i) { const int row = 8 * i + (lane >> 3), ch = lane & 7; const bf16x8 v = *(const bf16x8*)(src + (size_t)row * spitch + 8 * ch); *(LAS bf16x8*)(scr + row * 72 + 8 * ch) = v; }
;     LDS_WAIT();
; #pragma unroll
;     for (int cch = 0; cch < 8; ++cch) { u32x4 w; unsigned t[4];
; #pragma unroll
;         for (int e = 0; e < 4; ++e) { const unsigned lo = scr[(8 * cch + 2 * e) * 72 + lane], hi = scr[(8 * cch + 2 * e + 1) * 72 + lane]; t[e] = lo | (hi << 16); }
;         w.x = t[0]; w.y = t[1]; w.z = t[2]; w.w = t[3];
;         *(u32x4*)(dst + (size_t)lane * 2048 + 8 * cch) = w; }
;     LDS_WAIT();
; }
; __device__ __forceinline__ void post1(const KA& A, int L, LAS unsigned char* lds, int bid, int tid, int wave, int lane, int rep, int parts) {
;     ...
;     if (parts & 2) {
;         LAS bf16_t* scr = (LAS bf16_t*)(lds + wave * 16384);
;         for (int t = gwb; t < 12 * 4 * 32; t += NGW) {
;             const int st = t & 31, bl = (t >> 5) & 3, hs = t >> 7;
;             const int col = hs < 8 ? ZV_SB + 64 * hs : (hs < 10 ? ZSV + 64 * (hs - 8) : ZWV + 64 * (hs - 10));
;             bf16_t* dst = hs < 8 ? (bf16_t*)(ws + WS_VTSB) + ((size_t)(bl * 8 + hs) * 64) * 2048
;                         : (hs < 10 ? (bf16_t*)(ws + WS_VTSV) + ((size_t)(bl * 2 + hs - 8) * 64) * 2048 : (bf16_t*)(ws + WS_VTWV) + ((size_t)(bl * 2 + hs - 10) * 64) * 2048);
;             vt_tile(Z + ((size_t)bl * 2048 + 64 * st) * NINP + col, NINP, dst + 64 * st, scr, lane);
;         }
.LBB0_285:
	s_lshl_b64 s[0:1], s[14:15], 18
	s_add_u32 s14, s16, s0
	s_addc_u32 s15, s17, s1
	s_lshl_b32 s0, s20, 11
	s_and_b32 s16, s13, 0x7c0
	s_or_b32 s0, s0, s16
	s_mulk_i32 s0, 0x3200
	s_add_u32 s17, s2, s0
	s_addc_u32 s18, s3, 0
	s_ashr_i32 s11, s10, 31
	s_lshl_b64 s[0:1], s[10:11], 1
	s_add_u32 s0, s17, s0
	s_addc_u32 s1, s18, s1
	v_lshl_add_u64 v[20:21], s[0:1], 0, v[0:1]
	v_lshl_add_u64 v[24:25], v[20:21], 0, v[2:3]
	global_load_dwordx4 v[200:203], v[24:25], off
	s_lshl_b32 s10, s16, 1
	s_add_u32 s10, s14, s10
	s_addc_u32 s11, s15, 0
	s_add_i32 s12, s12, s78
	s_add_i32 s13, s13, s52
	s_cmpk_gt_i32 s12, 0x5ff
	v_lshl_add_u64 v[24:25], v[20:21], 0, v[4:5]
	global_load_dwordx4 v[204:207], v[24:25], off
	v_lshl_add_u64 v[24:25], v[20:21], 0, v[6:7]
	global_load_dwordx4 v[208:211], v[24:25], off
	v_lshl_add_u64 v[24:25], v[20:21], 0, v[8:9]
	global_load_dwordx4 v[212:215], v[24:25], off
	v_lshl_add_u64 v[24:25], v[20:21], 0, v[10:11]
	global_load_dwordx4 v[216:219], v[24:25], off
	v_lshl_add_u64 v[24:25], v[20:21], 0, v[12:13]
	global_load_dwordx4 v[220:223], v[24:25], off
	v_lshl_add_u64 v[24:25], v[20:21], 0, v[14:15]
	global_load_dwordx4 v[224:227], v[24:25], off
	v_lshl_add_u64 v[20:21], v[20:21], 0, v[16:17]
	global_load_dwordx4 v[228:231], v[20:21], off
	v_lshl_add_u64 v[20:21], s[10:11], 0, v[18:19]
	s_waitcnt vmcnt(7)
	ds_write_b128 v23, v[200:203]
	s_waitcnt vmcnt(6)
	ds_write_b128 v23, v[204:207] offset:1152
	s_waitcnt vmcnt(5)
	ds_write_b128 v23, v[208:211] offset:2304
	s_waitcnt vmcnt(4)
	ds_write_b128 v23, v[212:215] offset:3456
	s_waitcnt vmcnt(3)
	ds_write_b128 v23, v[216:219] offset:4608
	s_waitcnt vmcnt(2)
	ds_write_b128 v23, v[220:223] offset:5760
	s_waitcnt vmcnt(1)
	ds_write_b128 v23, v[224:227] offset:6912
	s_waitcnt vmcnt(0)
	ds_write_b128 v23, v[228:231] offset:8064
	s_waitcnt lgkmcnt(0)
	ds_read_u16 v24, v22
	ds_read_u16 v25, v22 offset:144
	s_waitcnt lgkmcnt(0)
	v_lshl_or_b32 v24, v25, 16, v24
	ds_read_u16 v25, v22 offset:288
	ds_read_u16 v26, v22 offset:432
	s_waitcnt lgkmcnt(0)
	v_lshl_or_b32 v25, v26, 16, v25
	ds_read_u16 v26, v22 offset:576
	ds_read_u16 v27, v22 offset:720
	s_waitcnt lgkmcnt(0)
	v_lshl_or_b32 v26, v27, 16, v26
	ds_read_u16 v27, v22 offset:864
	ds_read_u16 v28, v22 offset:1008
	s_waitcnt lgkmcnt(0)
	v_lshl_or_b32 v27, v28, 16, v27
	global_store_dwordx4 v[20:21], v[24:27], off
	ds_read_u16 v24, v22 offset:1152
	ds_read_u16 v25, v22 offset:1296
	s_waitcnt lgkmcnt(0)
	v_lshl_or_b32 v24, v25, 16, v24
	ds_read_u16 v25, v22 offset:1440
	ds_read_u16 v26, v22 offset:1584
	s_waitcnt lgkmcnt(0)
	v_lshl_or_b32 v25, v26, 16, v25
	ds_read_u16 v26, v22 offset:1728
	ds_read_u16 v27, v22 offset:1872
	s_waitcnt lgkmcnt(0)
	v_lshl_or_b32 v26, v27, 16, v26
	ds_read_u16 v27, v22 offset:2016
	ds_read_u16 v28, v22 offset:2160
	s_waitcnt lgkmcnt(0)
	v_lshl_or_b32 v27, v28, 16, v27
	global_store_dwordx4 v[20:21], v[24:27], off offset:16
	ds_read_u16 v24, v22 offset:2304
	ds_read_u16 v25, v22 offset:2448
	s_waitcnt lgkmcnt(0)
	v_lshl_or_b32 v24, v25, 16, v24
	ds_read_u16 v25, v22 offset:2592
	ds_read_u16 v26, v22 offset:2736
	s_waitcnt lgkmcnt(0)
	v_lshl_or_b32 v25, v26, 16, v25
	ds_read_u16 v26, v22 offset:2880
	ds_read_u16 v27, v22 offset:3024
	s_waitcnt lgkmcnt(0)
	v_lshl_or_b32 v26, v27, 16, v26
	ds_read_u16 v27, v22 offset:3168
	ds_read_u16 v28, v22 offset:3312
	s_waitcnt lgkmcnt(0)
	v_lshl_or_b32 v27, v28, 16, v27
	global_store_dwordx4 v[20:21], v[24:27], off offset:32
	ds_read_u16 v24, v22 offset:3456
	ds_read_u16 v25, v22 offset:3600
	s_waitcnt lgkmcnt(0)
	v_lshl_or_b32 v24, v25, 16, v24
	ds_read_u16 v25, v22 offset:3744
	ds_read_u16 v26, v22 offset:3888
	s_waitcnt lgkmcnt(0)
	v_lshl_or_b32 v25, v26, 16, v25
	ds_read_u16 v26, v22 offset:4032
	ds_read_u16 v27, v22 offset:4176
	s_waitcnt lgkmcnt(0)
	v_lshl_or_b32 v26, v27, 16, v26
	ds_read_u16 v27, v22 offset:4320
	ds_read_u16 v28, v22 offset:4464
	s_waitcnt lgkmcnt(0)
	v_lshl_or_b32 v27, v28, 16, v27
	global_store_dwordx4 v[20:21], v[24:27], off offset:48
	ds_read_u16 v24, v22 offset:4608
	ds_read_u16 v25, v22 offset:4752
	s_waitcnt lgkmcnt(0)
	v_lshl_or_b32 v24, v25, 16, v24
	ds_read_u16 v25, v22 offset:4896
	ds_read_u16 v26, v22 offset:5040
	s_waitcnt lgkmcnt(0)
	v_lshl_or_b32 v25, v26, 16, v25
	ds_read_u16 v26, v22 offset:5184
	ds_read_u16 v27, v22 offset:5328
	s_waitcnt lgkmcnt(0)
	v_lshl_or_b32 v26, v27, 16, v26
	ds_read_u16 v27, v22 offset:5472
	ds_read_u16 v28, v22 offset:5616
	s_waitcnt lgkmcnt(0)
	v_lshl_or_b32 v27, v28, 16, v27
	global_store_dwordx4 v[20:21], v[24:27], off offset:64
	ds_read_u16 v24, v22 offset:5760
	ds_read_u16 v25, v22 offset:5904
	s_waitcnt lgkmcnt(0)
	v_lshl_or_b32 v24, v25, 16, v24
	ds_read_u16 v25, v22 offset:6048
	ds_read_u16 v26, v22 offset:6192
	s_waitcnt lgkmcnt(0)
	v_lshl_or_b32 v25, v26, 16, v25
	ds_read_u16 v26, v22 offset:6336
	ds_read_u16 v27, v22 offset:6480
	s_waitcnt lgkmcnt(0)
	v_lshl_or_b32 v26, v27, 16, v26
	ds_read_u16 v27, v22 offset:6624
	ds_read_u16 v28, v22 offset:6768
	s_waitcnt lgkmcnt(0)
	v_lshl_or_b32 v27, v28, 16, v27
	global_store_dwordx4 v[20:21], v[24:27], off offset:80
	ds_read_u16 v24, v22 offset:6912
	ds_read_u16 v25, v22 offset:7056
	s_waitcnt lgkmcnt(0)
	v_lshl_or_b32 v24, v25, 16, v24
	ds_read_u16 v25, v22 offset:7200
	ds_read_u16 v26, v22 offset:7344
	s_waitcnt lgkmcnt(0)
	v_lshl_or_b32 v25, v26, 16, v25
	ds_read_u16 v26, v22 offset:7488
	ds_read_u16 v27, v22 offset:7632
	s_waitcnt lgkmcnt(0)
	v_lshl_or_b32 v26, v27, 16, v26
	ds_read_u16 v27, v22 offset:7776
	ds_read_u16 v28, v22 offset:7920
	s_waitcnt lgkmcnt(0)
	v_lshl_or_b32 v27, v28, 16, v27
	global_store_dwordx4 v[20:21], v[24:27], off offset:96
	ds_read_u16 v24, v22 offset:8064
	ds_read_u16 v25, v22 offset:8208
	s_waitcnt lgkmcnt(0)
	v_lshl_or_b32 v24, v25, 16, v24
	ds_read_u16 v25, v22 offset:8352
	ds_read_u16 v26, v22 offset:8496
	s_waitcnt lgkmcnt(0)
	v_lshl_or_b32 v25, v26, 16, v25
	ds_read_u16 v26, v22 offset:8640
	ds_read_u16 v27, v22 offset:8784
	s_waitcnt lgkmcnt(0)
	v_lshl_or_b32 v26, v27, 16, v26
	ds_read_u16 v27, v22 offset:8928
	ds_read_u16 v28, v22 offset:9072
	s_waitcnt lgkmcnt(0)
	v_lshl_or_b32 v27, v28, 16, v27
	global_store_dwordx4 v[20:21], v[24:27], off offset:112
	s_waitcnt lgkmcnt(0)
	s_cbranch_scc1 .LBB0_302

; #define LAS __attribute__((address_space(3)))
; #define LDS_WAIT() asm volatile("s_waitcnt lgkmcnt(0)" ::: "memory")
; __device__ __forceinline__ void vt_tile(const bf16_t* src, int spitch, bf16_t* dst, LAS bf16_t* scr, int lane) {
; #pragma unroll
;     for (int i = 0; i < 8; ++i) { const int row = 8 * i + (lane >> 3), ch = lane & 7; const bf16x8 v = *(const bf16x8*)(src + (size_t)row * spitch + 8 * ch); *(LAS bf16x8*)(scr + row * 72 + 8 * ch) = v; }
;     LDS_WAIT();
; #pragma unroll
;     for (int cch = 0; cch < 8; ++cch) { u32x4 w; unsigned t[4];
; #pragma unroll
;         for (int e = 0; e < 4; ++e) { const unsigned lo = scr[(8 * cch + 2 * e) * 72 + lane], hi = scr[(8 * cch + 2 * e + 1) * 72 + lane]; t[e] = lo | (hi << 16); }
;         w.x = t[0]; w.y = t[1]; w.z = t[2]; w.w = t[3];
;         *(u32x4*)(dst + (size_t)lane * 2048 + 8 * cch) = w; }
;     LDS_WAIT();
; }
; __device__ __forceinline__ void post2(const KA& A, int L, LAS unsigned char* lds, int bid, int tid, int wave, int lane) {
;     ...
;     {
;         LAS bf16_t* scr = (LAS bf16_t*)(lds + wave * 16384);
;         for (int t = gwb; t < 8 * 4 * 32; t += NGW) {
;             const int st = t & 31, bl = (t >> 5) & 3, hs = t >> 7;
;             vt_tile((const bf16_t*)(ws + WS_KVFULL) + ((size_t)bl * 2048 + 64 * st) * 1024 + 128 * hs + 64, 1024,
;                     (bf16_t*)(ws + WS_VTMLA) + ((size_t)(bl * 8 + hs) * 64) * 2048 + 64 * st, scr, lane);
;         }
.LBB0_959:
	s_bfe_u32 s0, s16, 0x20005
	s_and_b32 s7, s6, 0x7c0
	s_lshl_b32 s2, s7, 11
	s_lshl_b32 s3, s0, 22
	s_ashr_i32 s1, s16, 7
	s_or_b32 s2, s3, s2
	s_add_u32 s8, s90, s2
	s_addc_u32 s9, s91, 0
	s_and_b32 s2, s16, 0xffffff80
	s_ashr_i32 s3, s2, 31
	s_lshl_b64 s[2:3], s[2:3], 1
	s_add_u32 s8, s8, s2
	s_addc_u32 s9, s9, s3
	v_lshl_add_u64 v[22:23], s[8:9], 0, v[0:1]
	s_mov_b64 s[8:9], 0xc800080
	v_lshl_add_u64 v[26:27], v[22:23], 0, s[8:9]
	v_lshl_add_u64 v[22:23], v[26:27], 0, v[2:3]
	global_load_dwordx4 v[200:203], v[22:23], off
	s_lshl_b32 s0, s0, 3
	s_add_i32 s2, s0, s1
	s_ashr_i32 s3, s2, 31
	s_lshl_b64 s[2:3], s[2:3], 18
	s_add_u32 s0, s4, s2
	s_addc_u32 s1, s5, s3
	s_lshl_b32 s2, s7, 1
	s_add_u32 s2, s0, s2
	s_addc_u32 s3, s1, 0
	s_add_i32 s16, s16, s78
	s_add_i32 s6, s6, s52
	s_cmpk_gt_i32 s16, 0x3ff
	v_lshl_add_u64 v[22:23], v[26:27], 0, v[4:5]
	global_load_dwordx4 v[204:207], v[22:23], off
	v_lshl_add_u64 v[22:23], v[26:27], 0, v[6:7]
	global_load_dwordx4 v[208:211], v[22:23], off
	v_lshl_add_u64 v[22:23], v[26:27], 0, v[8:9]
	global_load_dwordx4 v[212:215], v[22:23], off
	v_lshl_add_u64 v[22:23], v[26:27], 0, v[10:11]
	global_load_dwordx4 v[216:219], v[22:23], off
	v_lshl_add_u64 v[22:23], v[26:27], 0, v[12:13]
	global_load_dwordx4 v[220:223], v[22:23], off
	v_lshl_add_u64 v[22:23], v[26:27], 0, v[14:15]
	global_load_dwordx4 v[224:227], v[22:23], off
	v_lshl_add_u64 v[22:23], v[26:27], 0, v[16:17]
	global_load_dwordx4 v[228:231], v[22:23], off
	v_lshl_add_u64 v[26:27], s[2:3], 0, v[18:19]
	s_waitcnt vmcnt(7)
	ds_write_b128 v21, v[200:203]
	s_waitcnt vmcnt(6)
	ds_write_b128 v21, v[204:207] offset:1152
	s_waitcnt vmcnt(5)
	ds_write_b128 v21, v[208:211] offset:2304
	s_waitcnt vmcnt(4)
	ds_write_b128 v21, v[212:215] offset:3456
	s_waitcnt vmcnt(3)
	ds_write_b128 v21, v[216:219] offset:4608
	s_waitcnt vmcnt(2)
	ds_write_b128 v21, v[220:223] offset:5760
	s_waitcnt vmcnt(1)
	ds_write_b128 v21, v[224:227] offset:6912
	s_waitcnt vmcnt(0)
	ds_write_b128 v21, v[228:231] offset:8064
	s_waitcnt lgkmcnt(0)
	ds_read_u16 v22, v20
	ds_read_u16 v23, v20 offset:144
	s_waitcnt lgkmcnt(0)
	v_lshl_or_b32 v22, v23, 16, v22
	ds_read_u16 v23, v20 offset:288
	ds_read_u16 v24, v20 offset:432
	s_waitcnt lgkmcnt(0)
	v_lshl_or_b32 v23, v24, 16, v23
	ds_read_u16 v24, v20 offset:576
	ds_read_u16 v25, v20 offset:720
	s_waitcnt lgkmcnt(0)
	v_lshl_or_b32 v24, v25, 16, v24
	ds_read_u16 v25, v20 offset:864
	ds_read_u16 v28, v20 offset:1008
	s_waitcnt lgkmcnt(0)
	v_lshl_or_b32 v25, v28, 16, v25
	global_store_dwordx4 v[26:27], v[22:25], off
	ds_read_u16 v22, v20 offset:1152
	ds_read_u16 v23, v20 offset:1296
	s_waitcnt lgkmcnt(0)
	v_lshl_or_b32 v22, v23, 16, v22
	ds_read_u16 v23, v20 offset:1440
	ds_read_u16 v24, v20 offset:1584
	s_waitcnt lgkmcnt(0)
	v_lshl_or_b32 v23, v24, 16, v23
	ds_read_u16 v24, v20 offset:1728
	ds_read_u16 v25, v20 offset:1872
	s_waitcnt lgkmcnt(0)
	v_lshl_or_b32 v24, v25, 16, v24
	ds_read_u16 v25, v20 offset:2016
	ds_read_u16 v28, v20 offset:2160
	s_waitcnt lgkmcnt(0)
	v_lshl_or_b32 v25, v28, 16, v25
	global_store_dwordx4 v[26:27], v[22:25], off offset:16
	ds_read_u16 v22, v20 offset:2304
	ds_read_u16 v23, v20 offset:2448
	s_waitcnt lgkmcnt(0)
	v_lshl_or_b32 v22, v23, 16, v22
	ds_read_u16 v23, v20 offset:2592
	ds_read_u16 v24, v20 offset:2736
	s_waitcnt lgkmcnt(0)
	v_lshl_or_b32 v23, v24, 16, v23
	ds_read_u16 v24, v20 offset:2880
	ds_read_u16 v25, v20 offset:3024
	s_waitcnt lgkmcnt(0)
	v_lshl_or_b32 v24, v25, 16, v24
	ds_read_u16 v25, v20 offset:3168
	ds_read_u16 v28, v20 offset:3312
	s_waitcnt lgkmcnt(0)
	v_lshl_or_b32 v25, v28, 16, v25
	global_store_dwordx4 v[26:27], v[22:25], off offset:32
	ds_read_u16 v22, v20 offset:3456
	ds_read_u16 v23, v20 offset:3600
	s_waitcnt lgkmcnt(0)
	v_lshl_or_b32 v22, v23, 16, v22
	ds_read_u16 v23, v20 offset:3744
	ds_read_u16 v24, v20 offset:3888
	s_waitcnt lgkmcnt(0)
	v_lshl_or_b32 v23, v24, 16, v23
	ds_read_u16 v24, v20 offset:4032
	ds_read_u16 v25, v20 offset:4176
	s_waitcnt lgkmcnt(0)
	v_lshl_or_b32 v24, v25, 16, v24
	ds_read_u16 v25, v20 offset:4320
	ds_read_u16 v28, v20 offset:4464
	s_waitcnt lgkmcnt(0)
	v_lshl_or_b32 v25, v28, 16, v25
	global_store_dwordx4 v[26:27], v[22:25], off offset:48
	ds_read_u16 v22, v20 offset:4608
	ds_read_u16 v23, v20 offset:4752
	s_waitcnt lgkmcnt(0)
	v_lshl_or_b32 v22, v23, 16, v22
	ds_read_u16 v23, v20 offset:4896
	ds_read_u16 v24, v20 offset:5040
	s_waitcnt lgkmcnt(0)
	v_lshl_or_b32 v23, v24, 16, v23
	ds_read_u16 v24, v20 offset:5184
	ds_read_u16 v25, v20 offset:5328
	s_waitcnt lgkmcnt(0)
	v_lshl_or_b32 v24, v25, 16, v24
	ds_read_u16 v25, v20 offset:5472
	ds_read_u16 v28, v20 offset:5616
	s_waitcnt lgkmcnt(0)
	v_lshl_or_b32 v25, v28, 16, v25
	global_store_dwordx4 v[26:27], v[22:25], off offset:64
	ds_read_u16 v22, v20 offset:5760
	ds_read_u16 v23, v20 offset:5904
	s_waitcnt lgkmcnt(0)
	v_lshl_or_b32 v22, v23, 16, v22
	ds_read_u16 v23, v20 offset:6048
	ds_read_u16 v24, v20 offset:6192
	s_waitcnt lgkmcnt(0)
	v_lshl_or_b32 v23, v24, 16, v23
	ds_read_u16 v24, v20 offset:6336
	ds_read_u16 v25, v20 offset:6480
	s_waitcnt lgkmcnt(0)
	v_lshl_or_b32 v24, v25, 16, v24
	ds_read_u16 v25, v20 offset:6624
	ds_read_u16 v28, v20 offset:6768
	s_waitcnt lgkmcnt(0)
	v_lshl_or_b32 v25, v28, 16, v25
	global_store_dwordx4 v[26:27], v[22:25], off offset:80
	ds_read_u16 v22, v20 offset:6912
	ds_read_u16 v23, v20 offset:7056
	s_waitcnt lgkmcnt(0)
	v_lshl_or_b32 v22, v23, 16, v22
	ds_read_u16 v23, v20 offset:7200
	ds_read_u16 v24, v20 offset:7344
	s_waitcnt lgkmcnt(0)
	v_lshl_or_b32 v23, v24, 16, v23
	ds_read_u16 v24, v20 offset:7488
	ds_read_u16 v25, v20 offset:7632
	s_waitcnt lgkmcnt(0)
	v_lshl_or_b32 v24, v25, 16, v24
	ds_read_u16 v25, v20 offset:7776
	ds_read_u16 v28, v20 offset:7920
	s_waitcnt lgkmcnt(0)
	v_lshl_or_b32 v25, v28, 16, v25
	global_store_dwordx4 v[26:27], v[22:25], off offset:96
	ds_read_u16 v22, v20 offset:8064
	ds_read_u16 v23, v20 offset:8208
	s_waitcnt lgkmcnt(0)
	v_lshl_or_b32 v22, v23, 16, v22
	ds_read_u16 v23, v20 offset:8352
	ds_read_u16 v24, v20 offset:8496
	s_waitcnt lgkmcnt(0)
	v_lshl_or_b32 v23, v24, 16, v23
	ds_read_u16 v24, v20 offset:8640
	ds_read_u16 v25, v20 offset:8784
	s_waitcnt lgkmcnt(0)
	v_lshl_or_b32 v24, v25, 16, v24
	ds_read_u16 v25, v20 offset:8928
	ds_read_u16 v28, v20 offset:9072
	s_waitcnt lgkmcnt(0)
	v_lshl_or_b32 v25, v28, 16, v25
	global_store_dwordx4 v[26:27], v[22:25], off offset:112
	s_waitcnt lgkmcnt(0)
	s_cbranch_scc0 .LBB0_959
